# GEMM K-loops: one static priority raise for the trailing wave half, per-block s_setprio flips removed (on top of nt4)
# speedup vs baseline: 1.0042x; 1.0042x over previous
; #define PG8_STAGE(bufoff, gbase, voff) do { _Pragma("unroll") for (int _i = 0; _i < 2; ++_i) \
;         __builtin_amdgcn_global_load_lds((const unsigned*)((const char*)(gbase) + (voff)[_i]), (PG8_LAS unsigned*)(lds + (bufoff) + ldsw + _i * 8192), 16, 0, 0); } while (0)
; #define PG8_LDA(dst, b, h) do { _Pragma("unroll") for (int m = 0; m < 4; ++m) _Pragma("unroll") for (int k = 0; k < 2; ++k) dst[m][k] = *(const PG8_LAS bf16x8*)(lds + PG8_SA(b, h) + aoff + m * 2048 + k * 1024); } while (0)
; #define PG8_LDB(dst, b, h) do { _Pragma("unroll") for (int n = 0; n < 2; ++n) _Pragma("unroll") for (int k = 0; k < 2; ++k) dst[n][k] = *(const PG8_LAS bf16x8*)(lds + PG8_SB(b, h) + boff + n * 2048 + k * 1024); } while (0)
; #define PG8_MMA(ai, bj, At, Bt) do { __builtin_amdgcn_s_setprio(1); _Pragma("unroll") for (int m = 0; m < 4; ++m) _Pragma("unroll") for (int n = 0; n < 2; ++n) _Pragma("unroll") for (int k = 0; k < 2; ++k) \
;         acc[ai][bj][m][n] = __builtin_amdgcn_mfma_f32_16x16x32_bf16(Bt[n][k], At[m][k], acc[ai][bj][m][n], 0, 0, 0); __builtin_amdgcn_s_setprio(0); } while (0)
; #define PG8_WAIT_V(n) asm volatile("s_waitcnt vmcnt(" #n ")" ::: "memory")
; #define PG8_WAIT_L(n) asm volatile("s_waitcnt lgkmcnt(" #n ")" ::: "memory")
; #define PG8_BAR __builtin_amdgcn_s_barrier()
; #define PG8_SCHED __builtin_amdgcn_sched_barrier(0)
; template <class Epi, class Sched, bool ALIGN_EPI = false, bool SP2 = false>
; __device__ __forceinline__ void gemm_phase(PG8_LAS unsigned char* lds, const Gemm g, const Sched& S, const Epi& E) {
;     ...
;             if constexpr (SP2) {
;             PG8_LDB(B0, 0, 0); PG8_LDB(B1, 0, 1); PG8_SCHED; PG8_LDA(At, 0, 0); PG8_STAGE(PG8_SA(1, 1), a1 + hstep, voffA);
;             PG8_WAIT_V(8); PG8_WAIT_L(0); PG8_BAR; PG8_MMA(0, 0, At, B0); PG8_MMA(0, 1, At, B1); PG8_BAR; PG8_SCHED;
;     ...
; #pragma unroll
;         for (int a = 0; a < 2; ++a)
; #pragma unroll
;             for (int b = 0; b < 2; ++b)
; #pragma unroll
;                 for (int m = 0; m < 4; ++m)
; #pragma unroll
;                     for (int n = 0; n < 2; ++n) acc[a][b][m][n] = (f32x4){0.f, 0.f, 0.f, 0.f};
;         cur = nxt; cA = nA; cB = nB; ++ui;
.LBB0_179:
	s_ashr_i32 s37, s36, 31
	s_lshl_b64 s[42:43], s[36:37], 20
	s_add_u32 s42, s16, s42
	s_addc_u32 s43, s17, s43
	s_and_b64 s[44:45], s[40:41], exec
	s_cselect_b32 s25, s43, s79
	s_cselect_b32 s27, s42, s78
	s_ashr_i32 s23, s22, 31
	s_lshl_b64 s[44:45], s[22:23], 20
	s_add_u32 s44, s4, s44
	s_addc_u32 s45, s5, s45
	s_and_b64 s[82:83], s[40:41], exec
	s_cselect_b32 s23, s45, s81
	s_cselect_b32 s37, s44, s80
	s_add_u32 s78, s78, 0x80080
	s_addc_u32 s79, s79, 0
	s_add_u32 s47, s80, 0x100
	v_mov_b32_e32 v2, 0
	s_addc_u32 s51, s81, 0
	s_mov_b32 s52, -2
	v_mov_b32_e32 v3, v2
	v_mov_b32_e32 v4, v2
	v_mov_b32_e32 v5, v2
	v_mov_b32_e32 v6, v2
	v_mov_b32_e32 v7, v2
	v_mov_b32_e32 v8, v2
	v_mov_b32_e32 v9, v2
	v_mov_b32_e32 v18, v2
	v_mov_b32_e32 v19, v2
	v_mov_b32_e32 v20, v2
	v_mov_b32_e32 v21, v2
	v_mov_b32_e32 v22, v2
	v_mov_b32_e32 v23, v2
	v_mov_b32_e32 v24, v2
	v_mov_b32_e32 v25, v2
	v_mov_b32_e32 v34, v2
	v_mov_b32_e32 v35, v2
	v_mov_b32_e32 v36, v2
	v_mov_b32_e32 v37, v2
	v_mov_b32_e32 v38, v2
	v_mov_b32_e32 v39, v2
	v_mov_b32_e32 v40, v2
	v_mov_b32_e32 v41, v2
	v_mov_b32_e32 v50, v2
	v_mov_b32_e32 v51, v2
	v_mov_b32_e32 v52, v2
	v_mov_b32_e32 v53, v2
	v_mov_b32_e32 v54, v2
	v_mov_b32_e32 v55, v2
	v_mov_b32_e32 v56, v2
	v_mov_b32_e32 v57, v2
	v_mov_b32_e32 v10, v2
	v_mov_b32_e32 v11, v2
	v_mov_b32_e32 v12, v2
	v_mov_b32_e32 v13, v2
	v_mov_b32_e32 v14, v2
	v_mov_b32_e32 v15, v2
	v_mov_b32_e32 v16, v2
	v_mov_b32_e32 v17, v2
	v_mov_b32_e32 v26, v2
	v_mov_b32_e32 v27, v2
	v_mov_b32_e32 v28, v2
	v_mov_b32_e32 v29, v2
	v_mov_b32_e32 v30, v2
	v_mov_b32_e32 v31, v2
	v_mov_b32_e32 v32, v2
	v_mov_b32_e32 v33, v2
	v_mov_b32_e32 v42, v2
	v_mov_b32_e32 v43, v2
	v_mov_b32_e32 v44, v2
	v_mov_b32_e32 v45, v2
	v_mov_b32_e32 v46, v2
	v_mov_b32_e32 v47, v2
	v_mov_b32_e32 v48, v2
	v_mov_b32_e32 v49, v2
	v_mov_b32_e32 v58, v2
	v_mov_b32_e32 v59, v2
	v_mov_b32_e32 v60, v2
	v_mov_b32_e32 v61, v2
	v_mov_b32_e32 v62, v2
	v_mov_b32_e32 v63, v2
	v_mov_b32_e32 v64, v2
	v_mov_b32_e32 v65, v2
	v_mov_b32_e32 v66, v2
	v_mov_b32_e32 v67, v2
	v_mov_b32_e32 v68, v2
	v_mov_b32_e32 v69, v2
	v_mov_b32_e32 v70, v2
	v_mov_b32_e32 v71, v2
	v_mov_b32_e32 v72, v2
	v_mov_b32_e32 v73, v2
	v_mov_b32_e32 v82, v2
	v_mov_b32_e32 v83, v2
	v_mov_b32_e32 v84, v2
	v_mov_b32_e32 v85, v2
	v_mov_b32_e32 v86, v2
	v_mov_b32_e32 v87, v2
	v_mov_b32_e32 v88, v2
	v_mov_b32_e32 v89, v2
	v_mov_b32_e32 v98, v2
	v_mov_b32_e32 v99, v2
	v_mov_b32_e32 v100, v2
	v_mov_b32_e32 v101, v2
	v_mov_b32_e32 v102, v2
	v_mov_b32_e32 v103, v2
	v_mov_b32_e32 v104, v2
	v_mov_b32_e32 v105, v2
	v_mov_b32_e32 v114, v2
	v_mov_b32_e32 v115, v2
	v_mov_b32_e32 v116, v2
	v_mov_b32_e32 v117, v2
	v_mov_b32_e32 v118, v2
	v_mov_b32_e32 v119, v2
	v_mov_b32_e32 v120, v2
	v_mov_b32_e32 v121, v2
	v_mov_b32_e32 v74, v2
	v_mov_b32_e32 v75, v2
	v_mov_b32_e32 v76, v2
	v_mov_b32_e32 v77, v2
	v_mov_b32_e32 v78, v2
	v_mov_b32_e32 v79, v2
	v_mov_b32_e32 v80, v2
	v_mov_b32_e32 v81, v2
	v_mov_b32_e32 v90, v2
	v_mov_b32_e32 v91, v2
	v_mov_b32_e32 v92, v2
	v_mov_b32_e32 v93, v2
	v_mov_b32_e32 v94, v2
	v_mov_b32_e32 v95, v2
	v_mov_b32_e32 v96, v2
	v_mov_b32_e32 v97, v2
	v_mov_b32_e32 v106, v2
	v_mov_b32_e32 v107, v2
	v_mov_b32_e32 v108, v2
	v_mov_b32_e32 v109, v2
	v_mov_b32_e32 v110, v2
	v_mov_b32_e32 v111, v2
	v_mov_b32_e32 v112, v2
	v_mov_b32_e32 v113, v2
	v_mov_b32_e32 v122, v2
	v_mov_b32_e32 v123, v2
	v_mov_b32_e32 v124, v2
	v_mov_b32_e32 v125, v2
	v_mov_b32_e32 v126, v2
	v_mov_b32_e32 v127, v2
	v_mov_b32_e32 v128, v2
	v_mov_b32_e32 v129, v2
	v_add_u32_e32 v242, s88, v177
	v_add_u32_e32 v243, s89, v177
	v_add_u32_e32 v244, s90, v177
	v_add_u32_e32 v245, 0x1c000, v177
	s_mov_b64 vcc, s[18:19]
	s_cbranch_vccnz .Lsp_out
	s_setprio 1
.Lsp_out:
.LBB0_180:
	ds_read_b128 v[130:133], v242
	ds_read_b128 v[134:137], v242 offset:1024
	ds_read_b128 v[138:141], v242 offset:2048
	ds_read_b128 v[142:145], v242 offset:3072
	ds_read_b128 v[146:149], v243
	ds_read_b128 v[150:153], v243 offset:1024
	ds_read_b128 v[164:167], v243 offset:2048
	ds_read_b128 v[168:171], v243 offset:3072
	s_add_u32 s80, s78, 0xfff80080
	s_addc_u32 s81, s79, -1
	s_cmp_eq_u32 s52, 28
	s_cselect_b32 s83, s25, s81
	s_cselect_b32 s82, s27, s80
	s_cselect_b32 s81, s23, s51
	s_cselect_b32 s80, s37, s47
	v_lshl_add_u64 v[204:205], s[78:79], 0, v[160:161]
	s_add_i32 m0, s7, 0xc000
	ds_read_b128 v[172:175], v179
	ds_read_b128 v[180:183], v179 offset:1024
	ds_read_b128 v[184:187], v179 offset:2048
	ds_read_b128 v[188:191], v179 offset:3072
	ds_read_b128 v[192:195], v179 offset:4096
	ds_read_b128 v[196:199], v179 offset:5120
	ds_read_b128 v[200:203], v179 offset:6144
	ds_read_b128 v[208:211], v179 offset:7168
	global_load_lds_dwordx4 v[204:205], off
	s_add_i32 m0, s7, 0xe000
	v_lshl_add_u64 v[204:205], s[78:79], 0, v[162:163]
	global_load_lds_dwordx4 v[204:205], off
	s_waitcnt vmcnt(8)
	s_waitcnt lgkmcnt(0)
	s_barrier
; #define PG8_STAGE(bufoff, gbase, voff) do { _Pragma("unroll") for (int _i = 0; _i < 2; ++_i) \
;         __builtin_amdgcn_global_load_lds((const unsigned*)((const char*)(gbase) + (voff)[_i]), (PG8_LAS unsigned*)(lds + (bufoff) + ldsw + _i * 8192), 16, 0, 0); } while (0)
; #define PG8_LDA(dst, b, h) do { _Pragma("unroll") for (int m = 0; m < 4; ++m) _Pragma("unroll") for (int k = 0; k < 2; ++k) dst[m][k] = *(const PG8_LAS bf16x8*)(lds + PG8_SA(b, h) + aoff + m * 2048 + k * 1024); } while (0)
; #define PG8_LDB(dst, b, h) do { _Pragma("unroll") for (int n = 0; n < 2; ++n) _Pragma("unroll") for (int k = 0; k < 2; ++k) dst[n][k] = *(const PG8_LAS bf16x8*)(lds + PG8_SB(b, h) + boff + n * 2048 + k * 1024); } while (0)
; #define PG8_MMA(ai, bj, At, Bt) do { __builtin_amdgcn_s_setprio(1); _Pragma("unroll") for (int m = 0; m < 4; ++m) _Pragma("unroll") for (int n = 0; n < 2; ++n) _Pragma("unroll") for (int k = 0; k < 2; ++k) \
;         acc[ai][bj][m][n] = __builtin_amdgcn_mfma_f32_16x16x32_bf16(Bt[n][k], At[m][k], acc[ai][bj][m][n], 0, 0, 0); __builtin_amdgcn_s_setprio(0); } while (0)
; #define PG8_WAIT_V(n) asm volatile("s_waitcnt vmcnt(" #n ")" ::: "memory")
; #define PG8_WAIT_L(n) asm volatile("s_waitcnt lgkmcnt(" #n ")" ::: "memory")
; #define PG8_BAR __builtin_amdgcn_s_barrier()
; #define PG8_SCHED __builtin_amdgcn_sched_barrier(0)
; template <class Epi, class Sched, bool ALIGN_EPI = false, bool SP2 = false>
; __device__ __forceinline__ void gemm_phase(PG8_LAS unsigned char* lds, const Gemm g, const Sched& S, const Epi& E) {
;     ...
;             PG8_LDB(B0, 0, 0); PG8_LDB(B1, 0, 1); PG8_SCHED; PG8_LDA(At, 0, 0); PG8_STAGE(PG8_SA(1, 1), a1 + hstep, voffA);
;             PG8_WAIT_V(8); PG8_WAIT_L(0); PG8_BAR; PG8_MMA(0, 0, At, B0); PG8_MMA(0, 1, At, B1); PG8_BAR; PG8_SCHED;
;             PG8_LDA(At, 0, 1); PG8_STAGE(PG8_SB(0, 0), b2, voffB); PG8_STAGE(PG8_SB(0, 1), b2 + hstep, voffB); PG8_STAGE(PG8_SA(0, 0), a2, voffA);
;             PG8_WAIT_V(8); PG8_WAIT_L(0); PG8_BAR; PG8_MMA(1, 0, At, B0); PG8_MMA(1, 1, At, B1); PG8_BAR; PG8_SCHED;
	v_mfma_f32_16x16x32_bf16 v[126:129], v[130:133], v[172:175], v[126:129]
	v_mfma_f32_16x16x32_bf16 v[122:125], v[138:141], v[172:175], v[122:125]
	v_mfma_f32_16x16x32_bf16 v[110:113], v[130:133], v[184:187], v[110:113]
	v_mfma_f32_16x16x32_bf16 v[106:109], v[138:141], v[184:187], v[106:109]
	v_mfma_f32_16x16x32_bf16 v[94:97], v[130:133], v[192:195], v[94:97]
	v_mfma_f32_16x16x32_bf16 v[90:93], v[138:141], v[192:195], v[90:93]
	v_mfma_f32_16x16x32_bf16 v[78:81], v[130:133], v[200:203], v[78:81]
	v_mfma_f32_16x16x32_bf16 v[74:77], v[138:141], v[200:203], v[74:77]
	v_mfma_f32_16x16x32_bf16 v[126:129], v[134:137], v[180:183], v[126:129]
	v_mfma_f32_16x16x32_bf16 v[122:125], v[142:145], v[180:183], v[122:125]
	v_mfma_f32_16x16x32_bf16 v[110:113], v[134:137], v[188:191], v[110:113]
	v_mfma_f32_16x16x32_bf16 v[106:109], v[142:145], v[188:191], v[106:109]
	v_mfma_f32_16x16x32_bf16 v[94:97], v[134:137], v[196:199], v[94:97]
	v_mfma_f32_16x16x32_bf16 v[90:93], v[142:145], v[196:199], v[90:93]
	v_mfma_f32_16x16x32_bf16 v[78:81], v[134:137], v[208:211], v[78:81]
	v_mfma_f32_16x16x32_bf16 v[74:77], v[142:145], v[208:211], v[74:77]
	v_mfma_f32_16x16x32_bf16 v[118:121], v[146:149], v[172:175], v[118:121]
	v_mfma_f32_16x16x32_bf16 v[114:117], v[164:167], v[172:175], v[114:117]
	v_mfma_f32_16x16x32_bf16 v[102:105], v[146:149], v[184:187], v[102:105]
	v_mfma_f32_16x16x32_bf16 v[98:101], v[164:167], v[184:187], v[98:101]
	v_mfma_f32_16x16x32_bf16 v[86:89], v[146:149], v[192:195], v[86:89]
	v_mfma_f32_16x16x32_bf16 v[82:85], v[164:167], v[192:195], v[82:85]
	v_mfma_f32_16x16x32_bf16 v[70:73], v[146:149], v[200:203], v[70:73]
	v_mfma_f32_16x16x32_bf16 v[66:69], v[164:167], v[200:203], v[66:69]
	v_mfma_f32_16x16x32_bf16 v[118:121], v[150:153], v[180:183], v[118:121]
	v_mfma_f32_16x16x32_bf16 v[114:117], v[168:171], v[180:183], v[114:117]
	v_mfma_f32_16x16x32_bf16 v[102:105], v[150:153], v[188:191], v[102:105]
	v_mfma_f32_16x16x32_bf16 v[98:101], v[168:171], v[188:191], v[98:101]
	v_mfma_f32_16x16x32_bf16 v[86:89], v[150:153], v[196:199], v[86:89]
	v_mfma_f32_16x16x32_bf16 v[82:85], v[168:171], v[196:199], v[82:85]
	v_mfma_f32_16x16x32_bf16 v[70:73], v[150:153], v[208:211], v[70:73]
	v_mfma_f32_16x16x32_bf16 v[66:69], v[168:171], v[208:211], v[66:69]
	s_barrier
	s_add_i32 s84, s88, s6
	v_lshl_add_u64 v[204:205], s[80:81], 0, v[0:1]
	s_mov_b32 m0, s84
	ds_read_b128 v[172:175], v179 offset:16384
	ds_read_b128 v[180:183], v179 offset:17408
	ds_read_b128 v[184:187], v179 offset:18432
	ds_read_b128 v[188:191], v179 offset:19456
	ds_read_b128 v[192:195], v179 offset:20480
	ds_read_b128 v[196:199], v179 offset:21504
	ds_read_b128 v[200:203], v179 offset:22528
	ds_read_b128 v[208:211], v179 offset:23552
	global_load_lds_dwordx4 v[204:205], off
	s_add_i32 m0, s84, 0x2000
	s_add_u32 s84, s80, 0x80000
	v_lshl_add_u64 v[212:213], s[80:81], 0, v[158:159]
	s_addc_u32 s85, s81, 0
	s_add_i32 s86, s89, s6
	global_load_lds_dwordx4 v[212:213], off
	v_lshl_add_u64 v[230:231], s[84:85], 0, v[0:1]
	s_mov_b32 m0, s86
	v_lshl_add_u64 v[232:233], s[82:83], 0, v[156:157]
	global_load_lds_dwordx4 v[230:231], off
	s_add_i32 m0, s86, 0x2000
	v_lshl_add_u64 v[230:231], s[84:85], 0, v[158:159]
	global_load_lds_dwordx4 v[230:231], off
	s_mov_b32 m0, s7
	v_lshl_add_u64 v[230:231], s[82:83], 0, v[154:155]
	global_load_lds_dwordx4 v[230:231], off
	s_mov_b32 m0, s8
	s_nop 0
	global_load_lds_dwordx4 v[232:233], off
	s_waitcnt vmcnt(8)
	s_waitcnt lgkmcnt(0)
	s_barrier
	v_mfma_f32_16x16x32_bf16 v[62:65], v[130:133], v[172:175], v[62:65]
	v_mfma_f32_16x16x32_bf16 v[58:61], v[138:141], v[172:175], v[58:61]
	v_mfma_f32_16x16x32_bf16 v[46:49], v[130:133], v[184:187], v[46:49]
	v_mfma_f32_16x16x32_bf16 v[42:45], v[138:141], v[184:187], v[42:45]
	v_mfma_f32_16x16x32_bf16 v[30:33], v[130:133], v[192:195], v[30:33]
	v_mfma_f32_16x16x32_bf16 v[26:29], v[138:141], v[192:195], v[26:29]
	v_mfma_f32_16x16x32_bf16 v[14:17], v[130:133], v[200:203], v[14:17]
	v_mfma_f32_16x16x32_bf16 v[10:13], v[138:141], v[200:203], v[10:13]
	v_mfma_f32_16x16x32_bf16 v[62:65], v[134:137], v[180:183], v[62:65]
	v_mfma_f32_16x16x32_bf16 v[58:61], v[142:145], v[180:183], v[58:61]
	v_mfma_f32_16x16x32_bf16 v[46:49], v[134:137], v[188:191], v[46:49]
	v_mfma_f32_16x16x32_bf16 v[42:45], v[142:145], v[188:191], v[42:45]
	v_mfma_f32_16x16x32_bf16 v[30:33], v[134:137], v[196:199], v[30:33]
	v_mfma_f32_16x16x32_bf16 v[26:29], v[142:145], v[196:199], v[26:29]
	v_mfma_f32_16x16x32_bf16 v[14:17], v[134:137], v[208:211], v[14:17]
	v_mfma_f32_16x16x32_bf16 v[10:13], v[142:145], v[208:211], v[10:13]
	v_mfma_f32_16x16x32_bf16 v[54:57], v[146:149], v[172:175], v[54:57]
	v_mfma_f32_16x16x32_bf16 v[50:53], v[164:167], v[172:175], v[50:53]
	v_mfma_f32_16x16x32_bf16 v[38:41], v[146:149], v[184:187], v[38:41]
	v_mfma_f32_16x16x32_bf16 v[34:37], v[164:167], v[184:187], v[34:37]
	v_mfma_f32_16x16x32_bf16 v[22:25], v[146:149], v[192:195], v[22:25]
	v_mfma_f32_16x16x32_bf16 v[18:21], v[164:167], v[192:195], v[18:21]
	v_mfma_f32_16x16x32_bf16 v[6:9], v[146:149], v[200:203], v[6:9]
	v_mfma_f32_16x16x32_bf16 v[2:5], v[164:167], v[200:203], v[2:5]
	v_mfma_f32_16x16x32_bf16 v[54:57], v[150:153], v[180:183], v[54:57]
	v_mfma_f32_16x16x32_bf16 v[50:53], v[168:171], v[180:183], v[50:53]
	v_mfma_f32_16x16x32_bf16 v[38:41], v[150:153], v[188:191], v[38:41]
	v_mfma_f32_16x16x32_bf16 v[34:37], v[168:171], v[188:191], v[34:37]
	v_mfma_f32_16x16x32_bf16 v[22:25], v[150:153], v[196:199], v[22:25]
	v_mfma_f32_16x16x32_bf16 v[18:21], v[168:171], v[196:199], v[18:21]
	v_mfma_f32_16x16x32_bf16 v[6:9], v[150:153], v[208:211], v[6:9]
	v_mfma_f32_16x16x32_bf16 v[2:5], v[168:171], v[208:211], v[2:5]
	s_barrier
; #define PG8_STAGE(bufoff, gbase, voff) do { _Pragma("unroll") for (int _i = 0; _i < 2; ++_i) \
;         __builtin_amdgcn_global_load_lds((const unsigned*)((const char*)(gbase) + (voff)[_i]), (PG8_LAS unsigned*)(lds + (bufoff) + ldsw + _i * 8192), 16, 0, 0); } while (0)
; #define PG8_LDA(dst, b, h) do { _Pragma("unroll") for (int m = 0; m < 4; ++m) _Pragma("unroll") for (int k = 0; k < 2; ++k) dst[m][k] = *(const PG8_LAS bf16x8*)(lds + PG8_SA(b, h) + aoff + m * 2048 + k * 1024); } while (0)
; #define PG8_LDB(dst, b, h) do { _Pragma("unroll") for (int n = 0; n < 2; ++n) _Pragma("unroll") for (int k = 0; k < 2; ++k) dst[n][k] = *(const PG8_LAS bf16x8*)(lds + PG8_SB(b, h) + boff + n * 2048 + k * 1024); } while (0)
; #define PG8_MMA(ai, bj, At, Bt) do { __builtin_amdgcn_s_setprio(1); _Pragma("unroll") for (int m = 0; m < 4; ++m) _Pragma("unroll") for (int n = 0; n < 2; ++n) _Pragma("unroll") for (int k = 0; k < 2; ++k) \
;         acc[ai][bj][m][n] = __builtin_amdgcn_mfma_f32_16x16x32_bf16(Bt[n][k], At[m][k], acc[ai][bj][m][n], 0, 0, 0); __builtin_amdgcn_s_setprio(0); } while (0)
; #define PG8_WAIT_V(n) asm volatile("s_waitcnt vmcnt(" #n ")" ::: "memory")
; #define PG8_WAIT_L(n) asm volatile("s_waitcnt lgkmcnt(" #n ")" ::: "memory")
; #define PG8_BAR __builtin_amdgcn_s_barrier()
; #define PG8_SCHED __builtin_amdgcn_sched_barrier(0)
; template <class Epi, class Sched, bool ALIGN_EPI = false, bool SP2 = false>
; __device__ __forceinline__ void gemm_phase(PG8_LAS unsigned char* lds, const Gemm g, const Sched& S, const Epi& E) {
;     ...
;             PG8_LDB(B0, 1, 0); PG8_LDB(B1, 1, 1); PG8_SCHED; PG8_LDA(At, 1, 0); PG8_STAGE(PG8_SA(0, 1), a2 + hstep, voffA);
;             PG8_WAIT_V(8); PG8_WAIT_L(0); PG8_BAR; PG8_MMA(0, 0, At, B0); PG8_MMA(0, 1, At, B1); PG8_BAR; PG8_SCHED;
;             PG8_LDA(At, 1, 1); PG8_STAGE(PG8_SB(1, 0), b3, voffB); PG8_STAGE(PG8_SB(1, 1), b3 + hstep, voffB); PG8_STAGE(PG8_SA(1, 0), a3, voffA);
;             PG8_WAIT_V(8); PG8_WAIT_L(0); PG8_BAR; PG8_MMA(1, 0, At, B0); PG8_MMA(1, 1, At, B1); PG8_BAR; PG8_SCHED;
	s_add_i32 s84, 0, 0x1c000
	ds_read_b128 v[130:133], v244
	ds_read_b128 v[134:137], v244 offset:1024
	ds_read_b128 v[138:141], v244 offset:2048
	ds_read_b128 v[142:145], v244 offset:3072
	ds_read_b128 v[146:149], v245
	ds_read_b128 v[150:153], v245 offset:1024
	ds_read_b128 v[164:167], v245 offset:2048
	ds_read_b128 v[168:171], v245 offset:3072
	s_add_u32 s82, s82, 0x80000
	s_addc_u32 s83, s83, 0
	s_mov_b32 m0, s9
	v_lshl_add_u64 v[234:235], s[82:83], 0, v[154:155]
	ds_read_b128 v[172:175], v179 offset:32768
	ds_read_b128 v[180:183], v179 offset:33792
	ds_read_b128 v[184:187], v179 offset:34816
	ds_read_b128 v[188:191], v179 offset:35840
	ds_read_b128 v[192:195], v179 offset:36864
	ds_read_b128 v[196:199], v179 offset:37888
	ds_read_b128 v[200:203], v179 offset:38912
	ds_read_b128 v[208:211], v179 offset:39936
	global_load_lds_dwordx4 v[234:235], off
	s_mov_b32 m0, s10
	v_lshl_add_u64 v[234:235], s[82:83], 0, v[156:157]
	global_load_lds_dwordx4 v[234:235], off
	s_waitcnt vmcnt(8)
	s_waitcnt lgkmcnt(0)
	s_barrier
	v_mfma_f32_16x16x32_bf16 v[126:129], v[130:133], v[172:175], v[126:129]
	v_mfma_f32_16x16x32_bf16 v[122:125], v[138:141], v[172:175], v[122:125]
	v_mfma_f32_16x16x32_bf16 v[110:113], v[130:133], v[184:187], v[110:113]
	v_mfma_f32_16x16x32_bf16 v[106:109], v[138:141], v[184:187], v[106:109]
	v_mfma_f32_16x16x32_bf16 v[94:97], v[130:133], v[192:195], v[94:97]
	v_mfma_f32_16x16x32_bf16 v[90:93], v[138:141], v[192:195], v[90:93]
	v_mfma_f32_16x16x32_bf16 v[78:81], v[130:133], v[200:203], v[78:81]
	v_mfma_f32_16x16x32_bf16 v[74:77], v[138:141], v[200:203], v[74:77]
	v_mfma_f32_16x16x32_bf16 v[126:129], v[134:137], v[180:183], v[126:129]
	v_mfma_f32_16x16x32_bf16 v[122:125], v[142:145], v[180:183], v[122:125]
	v_mfma_f32_16x16x32_bf16 v[110:113], v[134:137], v[188:191], v[110:113]
	v_mfma_f32_16x16x32_bf16 v[106:109], v[142:145], v[188:191], v[106:109]
	v_mfma_f32_16x16x32_bf16 v[94:97], v[134:137], v[196:199], v[94:97]
	v_mfma_f32_16x16x32_bf16 v[90:93], v[142:145], v[196:199], v[90:93]
	v_mfma_f32_16x16x32_bf16 v[78:81], v[134:137], v[208:211], v[78:81]
	v_mfma_f32_16x16x32_bf16 v[74:77], v[142:145], v[208:211], v[74:77]
	v_mfma_f32_16x16x32_bf16 v[118:121], v[146:149], v[172:175], v[118:121]
	v_mfma_f32_16x16x32_bf16 v[114:117], v[164:167], v[172:175], v[114:117]
	v_mfma_f32_16x16x32_bf16 v[102:105], v[146:149], v[184:187], v[102:105]
	v_mfma_f32_16x16x32_bf16 v[98:101], v[164:167], v[184:187], v[98:101]
	v_mfma_f32_16x16x32_bf16 v[86:89], v[146:149], v[192:195], v[86:89]
	v_mfma_f32_16x16x32_bf16 v[82:85], v[164:167], v[192:195], v[82:85]
	v_mfma_f32_16x16x32_bf16 v[70:73], v[146:149], v[200:203], v[70:73]
	v_mfma_f32_16x16x32_bf16 v[66:69], v[164:167], v[200:203], v[66:69]
	v_mfma_f32_16x16x32_bf16 v[118:121], v[150:153], v[180:183], v[118:121]
	v_mfma_f32_16x16x32_bf16 v[114:117], v[168:171], v[180:183], v[114:117]
	v_mfma_f32_16x16x32_bf16 v[102:105], v[150:153], v[188:191], v[102:105]
	v_mfma_f32_16x16x32_bf16 v[98:101], v[168:171], v[188:191], v[98:101]
	v_mfma_f32_16x16x32_bf16 v[86:89], v[150:153], v[196:199], v[86:89]
	v_mfma_f32_16x16x32_bf16 v[82:85], v[168:171], v[196:199], v[82:85]
	v_mfma_f32_16x16x32_bf16 v[70:73], v[150:153], v[208:211], v[70:73]
	v_mfma_f32_16x16x32_bf16 v[66:69], v[168:171], v[208:211], v[66:69]
	s_barrier
	s_add_i32 s82, s90, s6
	v_lshl_add_u64 v[204:205], v[204:205], 0, s[70:71]
	s_mov_b32 m0, s82
	ds_read_b128 v[172:175], v179 offset:49152
	ds_read_b128 v[180:183], v179 offset:50176
	ds_read_b128 v[184:187], v179 offset:51200
	ds_read_b128 v[188:191], v179 offset:52224
	ds_read_b128 v[192:195], v179 offset:53248
	ds_read_b128 v[196:199], v179 offset:54272
	ds_read_b128 v[200:203], v179 offset:55296
	ds_read_b128 v[208:211], v179 offset:56320
	global_load_lds_dwordx4 v[204:205], off
	s_add_i32 m0, s82, 0x2000
	s_add_u32 s80, s80, 0x80080
	v_lshl_add_u64 v[204:205], v[212:213], 0, s[70:71]
	s_addc_u32 s81, s81, 0
	s_add_i32 s82, s84, s6
	global_load_lds_dwordx4 v[204:205], off
	s_mov_b32 m0, s82
	v_lshl_add_u64 v[204:205], s[80:81], 0, v[0:1]
	global_load_lds_dwordx4 v[204:205], off
	s_add_i32 m0, s82, 0x2000
	v_lshl_add_u64 v[204:205], s[80:81], 0, v[158:159]
	global_load_lds_dwordx4 v[204:205], off
	s_mov_b32 m0, s12
	v_lshl_add_u64 v[204:205], v[230:231], 0, s[70:71]
	global_load_lds_dwordx4 v[204:205], off
	s_mov_b32 m0, s13
	v_lshl_add_u64 v[204:205], v[232:233], 0, s[70:71]
	global_load_lds_dwordx4 v[204:205], off
	s_waitcnt vmcnt(8)
	s_waitcnt lgkmcnt(0)
	s_barrier
	v_mfma_f32_16x16x32_bf16 v[62:65], v[130:133], v[172:175], v[62:65]
	v_mfma_f32_16x16x32_bf16 v[58:61], v[138:141], v[172:175], v[58:61]
	v_mfma_f32_16x16x32_bf16 v[46:49], v[130:133], v[184:187], v[46:49]
	v_mfma_f32_16x16x32_bf16 v[42:45], v[138:141], v[184:187], v[42:45]
	v_mfma_f32_16x16x32_bf16 v[30:33], v[130:133], v[192:195], v[30:33]
	v_mfma_f32_16x16x32_bf16 v[26:29], v[138:141], v[192:195], v[26:29]
	v_mfma_f32_16x16x32_bf16 v[14:17], v[130:133], v[200:203], v[14:17]
	v_mfma_f32_16x16x32_bf16 v[10:13], v[138:141], v[200:203], v[10:13]
	v_mfma_f32_16x16x32_bf16 v[62:65], v[134:137], v[180:183], v[62:65]
	v_mfma_f32_16x16x32_bf16 v[58:61], v[142:145], v[180:183], v[58:61]
	v_mfma_f32_16x16x32_bf16 v[46:49], v[134:137], v[188:191], v[46:49]
	v_mfma_f32_16x16x32_bf16 v[42:45], v[142:145], v[188:191], v[42:45]
	v_mfma_f32_16x16x32_bf16 v[30:33], v[134:137], v[196:199], v[30:33]
	v_mfma_f32_16x16x32_bf16 v[26:29], v[142:145], v[196:199], v[26:29]
	v_mfma_f32_16x16x32_bf16 v[14:17], v[134:137], v[208:211], v[14:17]
	v_mfma_f32_16x16x32_bf16 v[10:13], v[142:145], v[208:211], v[10:13]
	v_mfma_f32_16x16x32_bf16 v[54:57], v[146:149], v[172:175], v[54:57]
	v_mfma_f32_16x16x32_bf16 v[50:53], v[164:167], v[172:175], v[50:53]
	v_mfma_f32_16x16x32_bf16 v[38:41], v[146:149], v[184:187], v[38:41]
	v_mfma_f32_16x16x32_bf16 v[34:37], v[164:167], v[184:187], v[34:37]
	v_mfma_f32_16x16x32_bf16 v[22:25], v[146:149], v[192:195], v[22:25]
	v_mfma_f32_16x16x32_bf16 v[18:21], v[164:167], v[192:195], v[18:21]
	v_mfma_f32_16x16x32_bf16 v[6:9], v[146:149], v[200:203], v[6:9]
	v_mfma_f32_16x16x32_bf16 v[2:5], v[164:167], v[200:203], v[2:5]
	v_mfma_f32_16x16x32_bf16 v[54:57], v[150:153], v[180:183], v[54:57]
	v_mfma_f32_16x16x32_bf16 v[50:53], v[168:171], v[180:183], v[50:53]
	v_mfma_f32_16x16x32_bf16 v[38:41], v[150:153], v[188:191], v[38:41]
	v_mfma_f32_16x16x32_bf16 v[34:37], v[168:171], v[188:191], v[34:37]
	v_mfma_f32_16x16x32_bf16 v[22:25], v[150:153], v[196:199], v[22:25]
	v_mfma_f32_16x16x32_bf16 v[18:21], v[168:171], v[196:199], v[18:21]
	v_mfma_f32_16x16x32_bf16 v[6:9], v[150:153], v[208:211], v[6:9]
	v_mfma_f32_16x16x32_bf16 v[2:5], v[168:171], v[208:211], v[2:5]
	s_add_i32 s52, s52, 2
	s_add_u32 s78, s78, 0x100
	s_addc_u32 s79, s79, 0
	s_add_u32 s47, s47, 0x100
	s_addc_u32 s51, s51, 0
	s_cmp_gt_u32 s52, 29
	s_barrier
	s_cbranch_scc0 .LBB0_180
	s_setprio 0
	s_and_b64 vcc, exec, s[18:19]
	s_cbranch_vccz .LBB0_183
	s_barrier

; #define PG8_STAGE(bufoff, gbase, voff) do { _Pragma("unroll") for (int _i = 0; _i < 2; ++_i) \
;         __builtin_amdgcn_global_load_lds((const unsigned*)((const char*)(gbase) + (voff)[_i]), (PG8_LAS unsigned*)(lds + (bufoff) + ldsw + _i * 8192), 16, 0, 0); } while (0)
; #define PG8_LDA(dst, b, h) do { _Pragma("unroll") for (int m = 0; m < 4; ++m) _Pragma("unroll") for (int k = 0; k < 2; ++k) dst[m][k] = *(const PG8_LAS bf16x8*)(lds + PG8_SA(b, h) + aoff + m * 2048 + k * 1024); } while (0)
; #define PG8_LDB(dst, b, h) do { _Pragma("unroll") for (int n = 0; n < 2; ++n) _Pragma("unroll") for (int k = 0; k < 2; ++k) dst[n][k] = *(const PG8_LAS bf16x8*)(lds + PG8_SB(b, h) + boff + n * 2048 + k * 1024); } while (0)
; #define PG8_MMA(ai, bj, At, Bt) do { __builtin_amdgcn_s_setprio(1); _Pragma("unroll") for (int m = 0; m < 4; ++m) _Pragma("unroll") for (int n = 0; n < 2; ++n) _Pragma("unroll") for (int k = 0; k < 2; ++k) \
;         acc[ai][bj][m][n] = __builtin_amdgcn_mfma_f32_16x16x32_bf16(Bt[n][k], At[m][k], acc[ai][bj][m][n], 0, 0, 0); __builtin_amdgcn_s_setprio(0); } while (0)
; #define PG8_WAIT_V(n) asm volatile("s_waitcnt vmcnt(" #n ")" ::: "memory")
; #define PG8_WAIT_L(n) asm volatile("s_waitcnt lgkmcnt(" #n ")" ::: "memory")
; #define PG8_BAR __builtin_amdgcn_s_barrier()
; #define PG8_SCHED __builtin_amdgcn_sched_barrier(0)
; template <class Epi, class Sched, bool ALIGN_EPI = false, bool SP2 = false>
; __device__ __forceinline__ void gemm_phase(PG8_LAS unsigned char* lds, const Gemm g, const Sched& S, const Epi& E) {
;     ...
;             if constexpr (SP2) {
;             PG8_LDB(B0, 0, 0); PG8_LDB(B1, 0, 1); PG8_SCHED; PG8_LDA(At, 0, 0); PG8_STAGE(PG8_SA(1, 1), a1 + hstep, voffA);
;             PG8_WAIT_V(8); PG8_WAIT_L(0); PG8_BAR; PG8_MMA(0, 0, At, B0); PG8_MMA(0, 1, At, B1); PG8_BAR; PG8_SCHED;
;     ...
; #pragma unroll
;         for (int a = 0; a < 2; ++a)
; #pragma unroll
;             for (int b = 0; b < 2; ++b)
; #pragma unroll
;                 for (int m = 0; m < 4; ++m)
; #pragma unroll
;                     for (int n = 0; n < 2; ++n) acc[a][b][m][n] = (f32x4){0.f, 0.f, 0.f, 0.f};
;         cur = nxt; cA = nA; cB = nB; ++ui;
.Ltail_b:
	s_and_b64 s[34:35], s[38:39], exec
	s_cselect_b32 s17, s23, s41
	s_cselect_b32 s37, s22, s40
	s_add_u32 s34, s42, 0x80080
	s_addc_u32 s35, s43, 0
	s_add_u32 s44, s40, 0x100
	v_mov_b32_e32 v2, 0
	s_addc_u32 s45, s41, 0
	s_mov_b32 s46, -2
	v_mov_b32_e32 v3, v2
	v_mov_b32_e32 v4, v2
	v_mov_b32_e32 v5, v2
	v_mov_b32_e32 v6, v2
	v_mov_b32_e32 v7, v2
	v_mov_b32_e32 v8, v2
	v_mov_b32_e32 v9, v2
	v_mov_b32_e32 v18, v2
	v_mov_b32_e32 v19, v2
	v_mov_b32_e32 v20, v2
	v_mov_b32_e32 v21, v2
	v_mov_b32_e32 v22, v2
	v_mov_b32_e32 v23, v2
	v_mov_b32_e32 v24, v2
	v_mov_b32_e32 v25, v2
	v_mov_b32_e32 v34, v2
	v_mov_b32_e32 v35, v2
	v_mov_b32_e32 v36, v2
	v_mov_b32_e32 v37, v2
	v_mov_b32_e32 v38, v2
	v_mov_b32_e32 v39, v2
	v_mov_b32_e32 v40, v2
	v_mov_b32_e32 v41, v2
	v_mov_b32_e32 v50, v2
	v_mov_b32_e32 v51, v2
	v_mov_b32_e32 v52, v2
	v_mov_b32_e32 v53, v2
	v_mov_b32_e32 v54, v2
	v_mov_b32_e32 v55, v2
	v_mov_b32_e32 v56, v2
	v_mov_b32_e32 v57, v2
	v_mov_b32_e32 v10, v2
	v_mov_b32_e32 v11, v2
	v_mov_b32_e32 v12, v2
	v_mov_b32_e32 v13, v2
	v_mov_b32_e32 v14, v2
	v_mov_b32_e32 v15, v2
	v_mov_b32_e32 v16, v2
	v_mov_b32_e32 v17, v2
	v_mov_b32_e32 v26, v2
	v_mov_b32_e32 v27, v2
	v_mov_b32_e32 v28, v2
	v_mov_b32_e32 v29, v2
	v_mov_b32_e32 v30, v2
	v_mov_b32_e32 v31, v2
	v_mov_b32_e32 v32, v2
	v_mov_b32_e32 v33, v2
	v_mov_b32_e32 v42, v2
	v_mov_b32_e32 v43, v2
	v_mov_b32_e32 v44, v2
	v_mov_b32_e32 v45, v2
	v_mov_b32_e32 v46, v2
	v_mov_b32_e32 v47, v2
	v_mov_b32_e32 v48, v2
	v_mov_b32_e32 v49, v2
	v_mov_b32_e32 v58, v2
	v_mov_b32_e32 v59, v2
	v_mov_b32_e32 v60, v2
	v_mov_b32_e32 v61, v2
	v_mov_b32_e32 v62, v2
	v_mov_b32_e32 v63, v2
	v_mov_b32_e32 v64, v2
	v_mov_b32_e32 v65, v2
	v_mov_b32_e32 v66, v2
	v_mov_b32_e32 v67, v2
	v_mov_b32_e32 v68, v2
	v_mov_b32_e32 v69, v2
	v_mov_b32_e32 v70, v2
	v_mov_b32_e32 v71, v2
	v_mov_b32_e32 v72, v2
	v_mov_b32_e32 v73, v2
	v_mov_b32_e32 v82, v2
	v_mov_b32_e32 v83, v2
	v_mov_b32_e32 v84, v2
	v_mov_b32_e32 v85, v2
	v_mov_b32_e32 v86, v2
	v_mov_b32_e32 v87, v2
	v_mov_b32_e32 v88, v2
	v_mov_b32_e32 v89, v2
	v_mov_b32_e32 v98, v2
	v_mov_b32_e32 v99, v2
	v_mov_b32_e32 v100, v2
	v_mov_b32_e32 v101, v2
	v_mov_b32_e32 v102, v2
	v_mov_b32_e32 v103, v2
	v_mov_b32_e32 v104, v2
	v_mov_b32_e32 v105, v2
	v_mov_b32_e32 v122, v2
	v_mov_b32_e32 v123, v2
	v_mov_b32_e32 v124, v2
	v_mov_b32_e32 v125, v2
	v_mov_b32_e32 v126, v2
	v_mov_b32_e32 v127, v2
	v_mov_b32_e32 v128, v2
	v_mov_b32_e32 v129, v2
	v_mov_b32_e32 v74, v2
	v_mov_b32_e32 v75, v2
	v_mov_b32_e32 v76, v2
	v_mov_b32_e32 v77, v2
	v_mov_b32_e32 v78, v2
	v_mov_b32_e32 v79, v2
	v_mov_b32_e32 v80, v2
	v_mov_b32_e32 v81, v2
	v_mov_b32_e32 v90, v2
	v_mov_b32_e32 v91, v2
	v_mov_b32_e32 v92, v2
	v_mov_b32_e32 v93, v2
	v_mov_b32_e32 v94, v2
	v_mov_b32_e32 v95, v2
	v_mov_b32_e32 v96, v2
	v_mov_b32_e32 v97, v2
	v_mov_b32_e32 v106, v2
	v_mov_b32_e32 v107, v2
	v_mov_b32_e32 v108, v2
	v_mov_b32_e32 v109, v2
	v_mov_b32_e32 v110, v2
	v_mov_b32_e32 v111, v2
	v_mov_b32_e32 v112, v2
	v_mov_b32_e32 v113, v2
	v_mov_b32_e32 v138, v2
	v_mov_b32_e32 v139, v2
	v_mov_b32_e32 v140, v2
	v_mov_b32_e32 v141, v2
	v_mov_b32_e32 v142, v2
	v_mov_b32_e32 v143, v2
	v_mov_b32_e32 v144, v2
	v_mov_b32_e32 v145, v2
	v_add_u32_e32 v242, s88, v177
	v_add_u32_e32 v243, s89, v177
	v_add_u32_e32 v244, s90, v177
	v_add_u32_e32 v245, 0x1c000, v177
	s_mov_b64 vcc, s[2:3]
	s_cbranch_vccnz .Lsp_in
	s_setprio 1
.Lsp_in:
	s_cmp_eq_u32 s27, s85
	s_cbranch_scc1 .Ltail_loop
.LBB0_214:
	ds_read_b128 v[114:117], v242
	ds_read_b128 v[118:121], v242 offset:1024
	ds_read_b128 v[130:133], v242 offset:2048
	ds_read_b128 v[134:137], v242 offset:3072
	ds_read_b128 v[146:149], v243
	ds_read_b128 v[150:153], v243 offset:1024
	ds_read_b128 v[168:171], v243 offset:2048
	ds_read_b128 v[172:175], v243 offset:3072
	s_add_u32 s40, s34, 0xfff80080
	s_addc_u32 s41, s35, -1
	s_cmp_eq_u32 s46, 28
	s_cselect_b32 s43, s15, s41
	s_cselect_b32 s42, s19, s40
	s_cselect_b32 s41, s17, s45
	s_cselect_b32 s40, s37, s44
	v_lshl_add_u64 v[204:205], s[34:35], 0, v[164:165]
	s_add_i32 m0, s8, 0xc000
	ds_read_b128 v[180:183], v178
	ds_read_b128 v[184:187], v178 offset:1024
	ds_read_b128 v[188:191], v178 offset:2048
	ds_read_b128 v[192:195], v178 offset:3072
	ds_read_b128 v[196:199], v178 offset:4096
	ds_read_b128 v[200:203], v178 offset:5120
	ds_read_b128 v[208:211], v178 offset:6144
	ds_read_b128 v[230:233], v178 offset:7168
	global_load_lds_dwordx4 v[204:205], off
	s_add_i32 m0, s8, 0xe000
	v_lshl_add_u64 v[204:205], s[34:35], 0, v[166:167]
	global_load_lds_dwordx4 v[204:205], off
	s_waitcnt vmcnt(8)
	s_waitcnt lgkmcnt(0)
	s_barrier
; #define PG8_STAGE(bufoff, gbase, voff) do { _Pragma("unroll") for (int _i = 0; _i < 2; ++_i) \
;         __builtin_amdgcn_global_load_lds((const unsigned*)((const char*)(gbase) + (voff)[_i]), (PG8_LAS unsigned*)(lds + (bufoff) + ldsw + _i * 8192), 16, 0, 0); } while (0)
; #define PG8_LDA(dst, b, h) do { _Pragma("unroll") for (int m = 0; m < 4; ++m) _Pragma("unroll") for (int k = 0; k < 2; ++k) dst[m][k] = *(const PG8_LAS bf16x8*)(lds + PG8_SA(b, h) + aoff + m * 2048 + k * 1024); } while (0)
; #define PG8_LDB(dst, b, h) do { _Pragma("unroll") for (int n = 0; n < 2; ++n) _Pragma("unroll") for (int k = 0; k < 2; ++k) dst[n][k] = *(const PG8_LAS bf16x8*)(lds + PG8_SB(b, h) + boff + n * 2048 + k * 1024); } while (0)
; #define PG8_MMA(ai, bj, At, Bt) do { __builtin_amdgcn_s_setprio(1); _Pragma("unroll") for (int m = 0; m < 4; ++m) _Pragma("unroll") for (int n = 0; n < 2; ++n) _Pragma("unroll") for (int k = 0; k < 2; ++k) \
;         acc[ai][bj][m][n] = __builtin_amdgcn_mfma_f32_16x16x32_bf16(Bt[n][k], At[m][k], acc[ai][bj][m][n], 0, 0, 0); __builtin_amdgcn_s_setprio(0); } while (0)
; #define PG8_WAIT_V(n) asm volatile("s_waitcnt vmcnt(" #n ")" ::: "memory")
; #define PG8_WAIT_L(n) asm volatile("s_waitcnt lgkmcnt(" #n ")" ::: "memory")
; #define PG8_BAR __builtin_amdgcn_s_barrier()
; #define PG8_SCHED __builtin_amdgcn_sched_barrier(0)
; template <class Epi, class Sched, bool ALIGN_EPI = false, bool SP2 = false>
; __device__ __forceinline__ void gemm_phase(PG8_LAS unsigned char* lds, const Gemm g, const Sched& S, const Epi& E) {
;     ...
;             PG8_LDB(B0, 0, 0); PG8_LDB(B1, 0, 1); PG8_SCHED; PG8_LDA(At, 0, 0); PG8_STAGE(PG8_SA(1, 1), a1 + hstep, voffA);
;             PG8_WAIT_V(8); PG8_WAIT_L(0); PG8_BAR; PG8_MMA(0, 0, At, B0); PG8_MMA(0, 1, At, B1); PG8_BAR; PG8_SCHED;
;             PG8_LDA(At, 0, 1); PG8_STAGE(PG8_SB(0, 0), b2, voffB); PG8_STAGE(PG8_SB(0, 1), b2 + hstep, voffB); PG8_STAGE(PG8_SA(0, 0), a2, voffA);
;             PG8_WAIT_V(8); PG8_WAIT_L(0); PG8_BAR; PG8_MMA(1, 0, At, B0); PG8_MMA(1, 1, At, B1); PG8_BAR; PG8_SCHED;
	v_mfma_f32_16x16x32_bf16 v[142:145], v[114:117], v[180:183], v[142:145]
	v_mfma_f32_16x16x32_bf16 v[138:141], v[130:133], v[180:183], v[138:141]
	v_mfma_f32_16x16x32_bf16 v[110:113], v[114:117], v[188:191], v[110:113]
	v_mfma_f32_16x16x32_bf16 v[106:109], v[130:133], v[188:191], v[106:109]
	v_mfma_f32_16x16x32_bf16 v[94:97], v[114:117], v[196:199], v[94:97]
	v_mfma_f32_16x16x32_bf16 v[90:93], v[130:133], v[196:199], v[90:93]
	v_mfma_f32_16x16x32_bf16 v[78:81], v[114:117], v[208:211], v[78:81]
	v_mfma_f32_16x16x32_bf16 v[74:77], v[130:133], v[208:211], v[74:77]
	v_mfma_f32_16x16x32_bf16 v[142:145], v[118:121], v[184:187], v[142:145]
	v_mfma_f32_16x16x32_bf16 v[138:141], v[134:137], v[184:187], v[138:141]
	v_mfma_f32_16x16x32_bf16 v[110:113], v[118:121], v[192:195], v[110:113]
	v_mfma_f32_16x16x32_bf16 v[106:109], v[134:137], v[192:195], v[106:109]
	v_mfma_f32_16x16x32_bf16 v[94:97], v[118:121], v[200:203], v[94:97]
	v_mfma_f32_16x16x32_bf16 v[90:93], v[134:137], v[200:203], v[90:93]
	v_mfma_f32_16x16x32_bf16 v[78:81], v[118:121], v[230:233], v[78:81]
	v_mfma_f32_16x16x32_bf16 v[74:77], v[134:137], v[230:233], v[74:77]
	v_mfma_f32_16x16x32_bf16 v[126:129], v[146:149], v[180:183], v[126:129]
	v_mfma_f32_16x16x32_bf16 v[122:125], v[168:171], v[180:183], v[122:125]
	v_mfma_f32_16x16x32_bf16 v[102:105], v[146:149], v[188:191], v[102:105]
	v_mfma_f32_16x16x32_bf16 v[98:101], v[168:171], v[188:191], v[98:101]
	v_mfma_f32_16x16x32_bf16 v[86:89], v[146:149], v[196:199], v[86:89]
	v_mfma_f32_16x16x32_bf16 v[82:85], v[168:171], v[196:199], v[82:85]
	v_mfma_f32_16x16x32_bf16 v[70:73], v[146:149], v[208:211], v[70:73]
	v_mfma_f32_16x16x32_bf16 v[66:69], v[168:171], v[208:211], v[66:69]
	v_mfma_f32_16x16x32_bf16 v[126:129], v[150:153], v[184:187], v[126:129]
	v_mfma_f32_16x16x32_bf16 v[122:125], v[172:175], v[184:187], v[122:125]
	v_mfma_f32_16x16x32_bf16 v[102:105], v[150:153], v[192:195], v[102:105]
	v_mfma_f32_16x16x32_bf16 v[98:101], v[172:175], v[192:195], v[98:101]
	v_mfma_f32_16x16x32_bf16 v[86:89], v[150:153], v[200:203], v[86:89]
	v_mfma_f32_16x16x32_bf16 v[82:85], v[172:175], v[200:203], v[82:85]
	v_mfma_f32_16x16x32_bf16 v[70:73], v[150:153], v[230:233], v[70:73]
	v_mfma_f32_16x16x32_bf16 v[66:69], v[172:175], v[230:233], v[66:69]
	s_barrier
	s_add_i32 s47, s88, s6
	v_lshl_add_u64 v[204:205], s[40:41], 0, v[0:1]
	s_mov_b32 m0, s47
	ds_read_b128 v[180:183], v178 offset:16384
	ds_read_b128 v[184:187], v178 offset:17408
	ds_read_b128 v[188:191], v178 offset:18432
	ds_read_b128 v[192:195], v178 offset:19456
	ds_read_b128 v[196:199], v178 offset:20480
	ds_read_b128 v[200:203], v178 offset:21504
	ds_read_b128 v[208:211], v178 offset:22528
	ds_read_b128 v[230:233], v178 offset:23552
	global_load_lds_dwordx4 v[204:205], off
	s_add_i32 m0, s47, 0x2000
	s_add_u32 s50, s40, 0x80000
	v_lshl_add_u64 v[212:213], s[40:41], 0, v[154:155]
	s_addc_u32 s51, s41, 0
	s_add_i32 s47, s89, s6
	global_load_lds_dwordx4 v[212:213], off
	v_lshl_add_u64 v[234:235], s[50:51], 0, v[0:1]
	s_mov_b32 m0, s47
	v_lshl_add_u64 v[236:237], s[42:43], 0, v[156:157]
	global_load_lds_dwordx4 v[234:235], off
	s_add_i32 m0, s47, 0x2000
	v_lshl_add_u64 v[234:235], s[50:51], 0, v[154:155]
	global_load_lds_dwordx4 v[234:235], off
	s_mov_b32 m0, s8
	v_lshl_add_u64 v[234:235], s[42:43], 0, v[158:159]
	global_load_lds_dwordx4 v[234:235], off
	s_mov_b32 m0, s9
	s_nop 0
	global_load_lds_dwordx4 v[236:237], off
	s_waitcnt vmcnt(8)
	s_waitcnt lgkmcnt(0)
	s_barrier
	v_mfma_f32_16x16x32_bf16 v[62:65], v[114:117], v[180:183], v[62:65]
	v_mfma_f32_16x16x32_bf16 v[58:61], v[130:133], v[180:183], v[58:61]
	v_mfma_f32_16x16x32_bf16 v[46:49], v[114:117], v[188:191], v[46:49]
	v_mfma_f32_16x16x32_bf16 v[42:45], v[130:133], v[188:191], v[42:45]
	v_mfma_f32_16x16x32_bf16 v[30:33], v[114:117], v[196:199], v[30:33]
	v_mfma_f32_16x16x32_bf16 v[26:29], v[130:133], v[196:199], v[26:29]
	v_mfma_f32_16x16x32_bf16 v[14:17], v[114:117], v[208:211], v[14:17]
	v_mfma_f32_16x16x32_bf16 v[10:13], v[130:133], v[208:211], v[10:13]
	v_mfma_f32_16x16x32_bf16 v[62:65], v[118:121], v[184:187], v[62:65]
	v_mfma_f32_16x16x32_bf16 v[58:61], v[134:137], v[184:187], v[58:61]
	v_mfma_f32_16x16x32_bf16 v[46:49], v[118:121], v[192:195], v[46:49]
	v_mfma_f32_16x16x32_bf16 v[42:45], v[134:137], v[192:195], v[42:45]
	v_mfma_f32_16x16x32_bf16 v[30:33], v[118:121], v[200:203], v[30:33]
	v_mfma_f32_16x16x32_bf16 v[26:29], v[134:137], v[200:203], v[26:29]
	v_mfma_f32_16x16x32_bf16 v[14:17], v[118:121], v[230:233], v[14:17]
	v_mfma_f32_16x16x32_bf16 v[10:13], v[134:137], v[230:233], v[10:13]
	v_mfma_f32_16x16x32_bf16 v[54:57], v[146:149], v[180:183], v[54:57]
	v_mfma_f32_16x16x32_bf16 v[50:53], v[168:171], v[180:183], v[50:53]
	v_mfma_f32_16x16x32_bf16 v[38:41], v[146:149], v[188:191], v[38:41]
	v_mfma_f32_16x16x32_bf16 v[34:37], v[168:171], v[188:191], v[34:37]
	v_mfma_f32_16x16x32_bf16 v[22:25], v[146:149], v[196:199], v[22:25]
	v_mfma_f32_16x16x32_bf16 v[18:21], v[168:171], v[196:199], v[18:21]
	v_mfma_f32_16x16x32_bf16 v[6:9], v[146:149], v[208:211], v[6:9]
	v_mfma_f32_16x16x32_bf16 v[2:5], v[168:171], v[208:211], v[2:5]
	v_mfma_f32_16x16x32_bf16 v[54:57], v[150:153], v[184:187], v[54:57]
	v_mfma_f32_16x16x32_bf16 v[50:53], v[172:175], v[184:187], v[50:53]
	v_mfma_f32_16x16x32_bf16 v[38:41], v[150:153], v[192:195], v[38:41]
	v_mfma_f32_16x16x32_bf16 v[34:37], v[172:175], v[192:195], v[34:37]
	v_mfma_f32_16x16x32_bf16 v[22:25], v[150:153], v[200:203], v[22:25]
	v_mfma_f32_16x16x32_bf16 v[18:21], v[172:175], v[200:203], v[18:21]
	v_mfma_f32_16x16x32_bf16 v[6:9], v[150:153], v[230:233], v[6:9]
	v_mfma_f32_16x16x32_bf16 v[2:5], v[172:175], v[230:233], v[2:5]
	s_barrier
; #define PG8_STAGE(bufoff, gbase, voff) do { _Pragma("unroll") for (int _i = 0; _i < 2; ++_i) \
;         __builtin_amdgcn_global_load_lds((const unsigned*)((const char*)(gbase) + (voff)[_i]), (PG8_LAS unsigned*)(lds + (bufoff) + ldsw + _i * 8192), 16, 0, 0); } while (0)
; #define PG8_LDA(dst, b, h) do { _Pragma("unroll") for (int m = 0; m < 4; ++m) _Pragma("unroll") for (int k = 0; k < 2; ++k) dst[m][k] = *(const PG8_LAS bf16x8*)(lds + PG8_SA(b, h) + aoff + m * 2048 + k * 1024); } while (0)
; #define PG8_LDB(dst, b, h) do { _Pragma("unroll") for (int n = 0; n < 2; ++n) _Pragma("unroll") for (int k = 0; k < 2; ++k) dst[n][k] = *(const PG8_LAS bf16x8*)(lds + PG8_SB(b, h) + boff + n * 2048 + k * 1024); } while (0)
; #define PG8_MMA(ai, bj, At, Bt) do { __builtin_amdgcn_s_setprio(1); _Pragma("unroll") for (int m = 0; m < 4; ++m) _Pragma("unroll") for (int n = 0; n < 2; ++n) _Pragma("unroll") for (int k = 0; k < 2; ++k) \
;         acc[ai][bj][m][n] = __builtin_amdgcn_mfma_f32_16x16x32_bf16(Bt[n][k], At[m][k], acc[ai][bj][m][n], 0, 0, 0); __builtin_amdgcn_s_setprio(0); } while (0)
; #define PG8_WAIT_V(n) asm volatile("s_waitcnt vmcnt(" #n ")" ::: "memory")
; #define PG8_WAIT_L(n) asm volatile("s_waitcnt lgkmcnt(" #n ")" ::: "memory")
; #define PG8_BAR __builtin_amdgcn_s_barrier()
; #define PG8_SCHED __builtin_amdgcn_sched_barrier(0)
; template <class Epi, class Sched, bool ALIGN_EPI = false, bool SP2 = false>
; __device__ __forceinline__ void gemm_phase(PG8_LAS unsigned char* lds, const Gemm g, const Sched& S, const Epi& E) {
;     ...
;             PG8_LDB(B0, 1, 0); PG8_LDB(B1, 1, 1); PG8_SCHED; PG8_LDA(At, 1, 0); PG8_STAGE(PG8_SA(0, 1), a2 + hstep, voffA);
;             PG8_WAIT_V(8); PG8_WAIT_L(0); PG8_BAR; PG8_MMA(0, 0, At, B0); PG8_MMA(0, 1, At, B1); PG8_BAR; PG8_SCHED;
;             PG8_LDA(At, 1, 1); PG8_STAGE(PG8_SB(1, 0), b3, voffB); PG8_STAGE(PG8_SB(1, 1), b3 + hstep, voffB); PG8_STAGE(PG8_SA(1, 0), a3, voffA);
;             PG8_WAIT_V(8); PG8_WAIT_L(0); PG8_BAR; PG8_MMA(1, 0, At, B0); PG8_MMA(1, 1, At, B1); PG8_BAR; PG8_SCHED;
;     ...
;         if constexpr (ALIGN_EPI) { if (wr == 0) PG8_BAR; }
;         if constexpr (!Epi::AFTER_DRAIN) { E(acc, cur, wr, wc, fr, fq); S.done(cur); }
	s_add_i32 s47, 0, 0x1c000
	ds_read_b128 v[114:117], v244
	ds_read_b128 v[118:121], v244 offset:1024
	ds_read_b128 v[130:133], v244 offset:2048
	ds_read_b128 v[134:137], v244 offset:3072
	ds_read_b128 v[146:149], v245
	ds_read_b128 v[150:153], v245 offset:1024
	ds_read_b128 v[168:171], v245 offset:2048
	ds_read_b128 v[172:175], v245 offset:3072
	s_add_u32 s42, s42, 0x80000
	s_addc_u32 s43, s43, 0
	s_mov_b32 m0, s10
	v_lshl_add_u64 v[238:239], s[42:43], 0, v[158:159]
	ds_read_b128 v[180:183], v178 offset:32768
	ds_read_b128 v[184:187], v178 offset:33792
	ds_read_b128 v[188:191], v178 offset:34816
	ds_read_b128 v[192:195], v178 offset:35840
	ds_read_b128 v[196:199], v178 offset:36864
	ds_read_b128 v[200:203], v178 offset:37888
	ds_read_b128 v[208:211], v178 offset:38912
	ds_read_b128 v[230:233], v178 offset:39936
	global_load_lds_dwordx4 v[238:239], off
	s_mov_b32 m0, s11
	v_lshl_add_u64 v[238:239], s[42:43], 0, v[156:157]
	global_load_lds_dwordx4 v[238:239], off
	s_waitcnt vmcnt(8)
	s_waitcnt lgkmcnt(0)
	s_barrier
	v_mfma_f32_16x16x32_bf16 v[142:145], v[114:117], v[180:183], v[142:145]
	v_mfma_f32_16x16x32_bf16 v[138:141], v[130:133], v[180:183], v[138:141]
	v_mfma_f32_16x16x32_bf16 v[110:113], v[114:117], v[188:191], v[110:113]
	v_mfma_f32_16x16x32_bf16 v[106:109], v[130:133], v[188:191], v[106:109]
	v_mfma_f32_16x16x32_bf16 v[94:97], v[114:117], v[196:199], v[94:97]
	v_mfma_f32_16x16x32_bf16 v[90:93], v[130:133], v[196:199], v[90:93]
	v_mfma_f32_16x16x32_bf16 v[78:81], v[114:117], v[208:211], v[78:81]
	v_mfma_f32_16x16x32_bf16 v[74:77], v[130:133], v[208:211], v[74:77]
	v_mfma_f32_16x16x32_bf16 v[142:145], v[118:121], v[184:187], v[142:145]
	v_mfma_f32_16x16x32_bf16 v[138:141], v[134:137], v[184:187], v[138:141]
	v_mfma_f32_16x16x32_bf16 v[110:113], v[118:121], v[192:195], v[110:113]
	v_mfma_f32_16x16x32_bf16 v[106:109], v[134:137], v[192:195], v[106:109]
	v_mfma_f32_16x16x32_bf16 v[94:97], v[118:121], v[200:203], v[94:97]
	v_mfma_f32_16x16x32_bf16 v[90:93], v[134:137], v[200:203], v[90:93]
	v_mfma_f32_16x16x32_bf16 v[78:81], v[118:121], v[230:233], v[78:81]
	v_mfma_f32_16x16x32_bf16 v[74:77], v[134:137], v[230:233], v[74:77]
	v_mfma_f32_16x16x32_bf16 v[126:129], v[146:149], v[180:183], v[126:129]
	v_mfma_f32_16x16x32_bf16 v[122:125], v[168:171], v[180:183], v[122:125]
	v_mfma_f32_16x16x32_bf16 v[102:105], v[146:149], v[188:191], v[102:105]
	v_mfma_f32_16x16x32_bf16 v[98:101], v[168:171], v[188:191], v[98:101]
	v_mfma_f32_16x16x32_bf16 v[86:89], v[146:149], v[196:199], v[86:89]
	v_mfma_f32_16x16x32_bf16 v[82:85], v[168:171], v[196:199], v[82:85]
	v_mfma_f32_16x16x32_bf16 v[70:73], v[146:149], v[208:211], v[70:73]
	v_mfma_f32_16x16x32_bf16 v[66:69], v[168:171], v[208:211], v[66:69]
	v_mfma_f32_16x16x32_bf16 v[126:129], v[150:153], v[184:187], v[126:129]
	v_mfma_f32_16x16x32_bf16 v[122:125], v[172:175], v[184:187], v[122:125]
	v_mfma_f32_16x16x32_bf16 v[102:105], v[150:153], v[192:195], v[102:105]
	v_mfma_f32_16x16x32_bf16 v[98:101], v[172:175], v[192:195], v[98:101]
	v_mfma_f32_16x16x32_bf16 v[86:89], v[150:153], v[200:203], v[86:89]
	v_mfma_f32_16x16x32_bf16 v[82:85], v[172:175], v[200:203], v[82:85]
	v_mfma_f32_16x16x32_bf16 v[70:73], v[150:153], v[230:233], v[70:73]
	v_mfma_f32_16x16x32_bf16 v[66:69], v[172:175], v[230:233], v[66:69]
	s_barrier
	s_add_i32 s42, s90, s6
	v_lshl_add_u64 v[204:205], v[204:205], 0, s[70:71]
	s_mov_b32 m0, s42
	ds_read_b128 v[180:183], v178 offset:49152
	ds_read_b128 v[184:187], v178 offset:50176
	ds_read_b128 v[188:191], v178 offset:51200
	ds_read_b128 v[192:195], v178 offset:52224
	ds_read_b128 v[196:199], v178 offset:53248
	ds_read_b128 v[200:203], v178 offset:54272
	ds_read_b128 v[208:211], v178 offset:55296
	ds_read_b128 v[230:233], v178 offset:56320
	global_load_lds_dwordx4 v[204:205], off
	s_add_i32 m0, s42, 0x2000
	s_add_u32 s40, s40, 0x80080
	v_lshl_add_u64 v[204:205], v[212:213], 0, s[70:71]
	s_addc_u32 s41, s41, 0
	s_add_i32 s42, s47, s6
	global_load_lds_dwordx4 v[204:205], off
	s_mov_b32 m0, s42
	v_lshl_add_u64 v[204:205], s[40:41], 0, v[0:1]
	global_load_lds_dwordx4 v[204:205], off
	s_add_i32 m0, s42, 0x2000
	v_lshl_add_u64 v[204:205], s[40:41], 0, v[154:155]
	global_load_lds_dwordx4 v[204:205], off
	s_mov_b32 m0, s13
	v_lshl_add_u64 v[204:205], v[234:235], 0, s[70:71]
	global_load_lds_dwordx4 v[204:205], off
	s_mov_b32 m0, s25
	v_lshl_add_u64 v[204:205], v[236:237], 0, s[70:71]
	global_load_lds_dwordx4 v[204:205], off
	s_waitcnt vmcnt(8)
	s_waitcnt lgkmcnt(0)
	s_barrier
	v_mfma_f32_16x16x32_bf16 v[62:65], v[114:117], v[180:183], v[62:65]
	v_mfma_f32_16x16x32_bf16 v[58:61], v[130:133], v[180:183], v[58:61]
	v_mfma_f32_16x16x32_bf16 v[46:49], v[114:117], v[188:191], v[46:49]
	v_mfma_f32_16x16x32_bf16 v[42:45], v[130:133], v[188:191], v[42:45]
	v_mfma_f32_16x16x32_bf16 v[30:33], v[114:117], v[196:199], v[30:33]
	v_mfma_f32_16x16x32_bf16 v[26:29], v[130:133], v[196:199], v[26:29]
	v_mfma_f32_16x16x32_bf16 v[14:17], v[114:117], v[208:211], v[14:17]
	v_mfma_f32_16x16x32_bf16 v[10:13], v[130:133], v[208:211], v[10:13]
	v_mfma_f32_16x16x32_bf16 v[62:65], v[118:121], v[184:187], v[62:65]
	v_mfma_f32_16x16x32_bf16 v[58:61], v[134:137], v[184:187], v[58:61]
	v_mfma_f32_16x16x32_bf16 v[46:49], v[118:121], v[192:195], v[46:49]
	v_mfma_f32_16x16x32_bf16 v[42:45], v[134:137], v[192:195], v[42:45]
	v_mfma_f32_16x16x32_bf16 v[30:33], v[118:121], v[200:203], v[30:33]
	v_mfma_f32_16x16x32_bf16 v[26:29], v[134:137], v[200:203], v[26:29]
	v_mfma_f32_16x16x32_bf16 v[14:17], v[118:121], v[230:233], v[14:17]
	v_mfma_f32_16x16x32_bf16 v[10:13], v[134:137], v[230:233], v[10:13]
	v_mfma_f32_16x16x32_bf16 v[54:57], v[146:149], v[180:183], v[54:57]
	v_mfma_f32_16x16x32_bf16 v[50:53], v[168:171], v[180:183], v[50:53]
	v_mfma_f32_16x16x32_bf16 v[38:41], v[146:149], v[188:191], v[38:41]
	v_mfma_f32_16x16x32_bf16 v[34:37], v[168:171], v[188:191], v[34:37]
	v_mfma_f32_16x16x32_bf16 v[22:25], v[146:149], v[196:199], v[22:25]
	v_mfma_f32_16x16x32_bf16 v[18:21], v[168:171], v[196:199], v[18:21]
	v_mfma_f32_16x16x32_bf16 v[6:9], v[146:149], v[208:211], v[6:9]
	v_mfma_f32_16x16x32_bf16 v[2:5], v[168:171], v[208:211], v[2:5]
	v_mfma_f32_16x16x32_bf16 v[54:57], v[150:153], v[184:187], v[54:57]
	v_mfma_f32_16x16x32_bf16 v[50:53], v[172:175], v[184:187], v[50:53]
	v_mfma_f32_16x16x32_bf16 v[38:41], v[150:153], v[192:195], v[38:41]
	v_mfma_f32_16x16x32_bf16 v[34:37], v[172:175], v[192:195], v[34:37]
	v_mfma_f32_16x16x32_bf16 v[22:25], v[150:153], v[200:203], v[22:25]
	v_mfma_f32_16x16x32_bf16 v[18:21], v[172:175], v[200:203], v[18:21]
	v_mfma_f32_16x16x32_bf16 v[6:9], v[150:153], v[230:233], v[6:9]
	v_mfma_f32_16x16x32_bf16 v[2:5], v[172:175], v[230:233], v[2:5]
	s_add_i32 s46, s46, 2
	s_add_u32 s34, s34, 0x100
	s_addc_u32 s35, s35, 0
	s_add_u32 s44, s44, 0x100
	s_addc_u32 s45, s45, 0
	s_cmp_gt_u32 s46, 29
	s_barrier
	s_cbranch_scc0 .LBB0_214
.Ltail_join:
	s_setprio 0
	s_and_b64 vcc, exec, s[2:3]
	s_cbranch_vccz .LBB0_217
	s_barrier

; #define PG8_STAGE(bufoff, gbase, voff) do { _Pragma("unroll") for (int _i = 0; _i < 2; ++_i) \
;         __builtin_amdgcn_global_load_lds((const unsigned*)((const char*)(gbase) + (voff)[_i]), (PG8_LAS unsigned*)(lds + (bufoff) + ldsw + _i * 8192), 16, 0, 0); } while (0)
; #define PG8_LDA(dst, b, h) do { _Pragma("unroll") for (int m = 0; m < 4; ++m) _Pragma("unroll") for (int k = 0; k < 2; ++k) dst[m][k] = *(const PG8_LAS bf16x8*)(lds + PG8_SA(b, h) + aoff + m * 2048 + k * 1024); } while (0)
; #define PG8_LDB(dst, b, h) do { _Pragma("unroll") for (int n = 0; n < 2; ++n) _Pragma("unroll") for (int k = 0; k < 2; ++k) dst[n][k] = *(const PG8_LAS bf16x8*)(lds + PG8_SB(b, h) + boff + n * 2048 + k * 1024); } while (0)
; #define PG8_MMA(ai, bj, At, Bt) do { __builtin_amdgcn_s_setprio(1); _Pragma("unroll") for (int m = 0; m < 4; ++m) _Pragma("unroll") for (int n = 0; n < 2; ++n) _Pragma("unroll") for (int k = 0; k < 2; ++k) \
;         acc[ai][bj][m][n] = __builtin_amdgcn_mfma_f32_16x16x32_bf16(Bt[n][k], At[m][k], acc[ai][bj][m][n], 0, 0, 0); __builtin_amdgcn_s_setprio(0); } while (0)
; #define PG8_WAIT_V(n) asm volatile("s_waitcnt vmcnt(" #n ")" ::: "memory")
; #define PG8_WAIT_L(n) asm volatile("s_waitcnt lgkmcnt(" #n ")" ::: "memory")
; #define PG8_BAR __builtin_amdgcn_s_barrier()
; #define PG8_SCHED __builtin_amdgcn_sched_barrier(0)
; template <class Epi, class Sched, bool ALIGN_EPI = false, bool SP2 = false>
; __device__ __forceinline__ void gemm_phase(PG8_LAS unsigned char* lds, const Gemm g, const Sched& S, const Epi& E) {
;     ...
;             PG8_LDB(B0, 0, 0); PG8_LDB(B1, 0, 1); PG8_SCHED; PG8_LDA(At, 0, 0); PG8_STAGE(PG8_SA(1, 1), a1 + hstep, voffA);
;             PG8_WAIT_V(8); PG8_WAIT_L(0); PG8_BAR; PG8_MMA(0, 0, At, B0); PG8_MMA(0, 1, At, B1); PG8_BAR; PG8_SCHED;
;             PG8_LDA(At, 0, 1); PG8_STAGE(PG8_SB(0, 0), b2, voffB); PG8_STAGE(PG8_SB(0, 1), b2 + hstep, voffB); PG8_STAGE(PG8_SA(0, 0), a2, voffA);
;             PG8_WAIT_V(8); PG8_WAIT_L(0); PG8_BAR; PG8_MMA(1, 0, At, B0); PG8_MMA(1, 1, At, B1); PG8_BAR; PG8_SCHED;
.Ltail_loop:
	ds_read_b128 v[114:117], v242
	ds_read_b128 v[118:121], v242 offset:1024
	ds_read_b128 v[130:133], v242 offset:2048
	ds_read_b128 v[134:137], v242 offset:3072
	s_add_u32 s40, s34, 0xfff80080
	s_addc_u32 s41, s35, -1
	s_cmp_eq_u32 s46, 28
	s_cselect_b32 s43, s15, s41
	s_cselect_b32 s42, s19, s40
	s_cselect_b32 s41, s17, s45
	s_cselect_b32 s40, s37, s44
	v_lshl_add_u64 v[204:205], s[34:35], 0, v[164:165]
	s_add_i32 m0, s8, 0xc000
	ds_read_b128 v[180:183], v178
	ds_read_b128 v[184:187], v178 offset:1024
	ds_read_b128 v[188:191], v178 offset:2048
	ds_read_b128 v[192:195], v178 offset:3072
	ds_read_b128 v[196:199], v178 offset:4096
	ds_read_b128 v[200:203], v178 offset:5120
	ds_read_b128 v[208:211], v178 offset:6144
	ds_read_b128 v[230:233], v178 offset:7168
	global_load_lds_dwordx4 v[204:205], off
	s_add_i32 m0, s8, 0xe000
	v_lshl_add_u64 v[204:205], s[34:35], 0, v[166:167]
	global_load_lds_dwordx4 v[204:205], off
	s_waitcnt vmcnt(8)
	s_waitcnt lgkmcnt(0)
	s_barrier
	v_mfma_f32_16x16x32_bf16 v[142:145], v[114:117], v[180:183], v[142:145]
	v_mfma_f32_16x16x32_bf16 v[138:141], v[130:133], v[180:183], v[138:141]
	v_mfma_f32_16x16x32_bf16 v[110:113], v[114:117], v[188:191], v[110:113]
	v_mfma_f32_16x16x32_bf16 v[106:109], v[130:133], v[188:191], v[106:109]
	v_mfma_f32_16x16x32_bf16 v[94:97], v[114:117], v[196:199], v[94:97]
	v_mfma_f32_16x16x32_bf16 v[90:93], v[130:133], v[196:199], v[90:93]
	v_mfma_f32_16x16x32_bf16 v[78:81], v[114:117], v[208:211], v[78:81]
	v_mfma_f32_16x16x32_bf16 v[74:77], v[130:133], v[208:211], v[74:77]
	v_mfma_f32_16x16x32_bf16 v[142:145], v[118:121], v[184:187], v[142:145]
	v_mfma_f32_16x16x32_bf16 v[138:141], v[134:137], v[184:187], v[138:141]
	v_mfma_f32_16x16x32_bf16 v[110:113], v[118:121], v[192:195], v[110:113]
	v_mfma_f32_16x16x32_bf16 v[106:109], v[134:137], v[192:195], v[106:109]
	v_mfma_f32_16x16x32_bf16 v[94:97], v[118:121], v[200:203], v[94:97]
	v_mfma_f32_16x16x32_bf16 v[90:93], v[134:137], v[200:203], v[90:93]
	v_mfma_f32_16x16x32_bf16 v[78:81], v[118:121], v[230:233], v[78:81]
	v_mfma_f32_16x16x32_bf16 v[74:77], v[134:137], v[230:233], v[74:77]
	s_barrier
	s_add_i32 s47, s88, s6
	v_lshl_add_u64 v[204:205], s[40:41], 0, v[0:1]
	s_mov_b32 m0, s47
	ds_read_b128 v[180:183], v178 offset:16384
	ds_read_b128 v[184:187], v178 offset:17408
	ds_read_b128 v[188:191], v178 offset:18432
	ds_read_b128 v[192:195], v178 offset:19456
	ds_read_b128 v[196:199], v178 offset:20480
	ds_read_b128 v[200:203], v178 offset:21504
	ds_read_b128 v[208:211], v178 offset:22528
	ds_read_b128 v[230:233], v178 offset:23552
	global_load_lds_dwordx4 v[204:205], off
	s_add_i32 m0, s47, 0x2000
	s_add_u32 s50, s40, 0x80000
	v_lshl_add_u64 v[212:213], s[40:41], 0, v[154:155]
	s_addc_u32 s51, s41, 0
	s_add_i32 s47, s89, s6
	global_load_lds_dwordx4 v[212:213], off
	v_lshl_add_u64 v[234:235], s[50:51], 0, v[0:1]
	s_mov_b32 m0, s47
	v_lshl_add_u64 v[236:237], s[42:43], 0, v[156:157]
	global_load_lds_dwordx4 v[234:235], off
	s_add_i32 m0, s47, 0x2000
	v_lshl_add_u64 v[234:235], s[50:51], 0, v[154:155]
	global_load_lds_dwordx4 v[234:235], off
	s_mov_b32 m0, s8
	v_lshl_add_u64 v[234:235], s[42:43], 0, v[158:159]
	global_load_lds_dwordx4 v[234:235], off
	s_mov_b32 m0, s9
	s_nop 0
	global_load_lds_dwordx4 v[236:237], off
	s_waitcnt vmcnt(8)
	s_waitcnt lgkmcnt(0)
	s_barrier
	v_mfma_f32_16x16x32_bf16 v[62:65], v[114:117], v[180:183], v[62:65]
	v_mfma_f32_16x16x32_bf16 v[58:61], v[130:133], v[180:183], v[58:61]
	v_mfma_f32_16x16x32_bf16 v[46:49], v[114:117], v[188:191], v[46:49]
	v_mfma_f32_16x16x32_bf16 v[42:45], v[130:133], v[188:191], v[42:45]
	v_mfma_f32_16x16x32_bf16 v[30:33], v[114:117], v[196:199], v[30:33]
	v_mfma_f32_16x16x32_bf16 v[26:29], v[130:133], v[196:199], v[26:29]
	v_mfma_f32_16x16x32_bf16 v[14:17], v[114:117], v[208:211], v[14:17]
	v_mfma_f32_16x16x32_bf16 v[10:13], v[130:133], v[208:211], v[10:13]
	v_mfma_f32_16x16x32_bf16 v[62:65], v[118:121], v[184:187], v[62:65]
	v_mfma_f32_16x16x32_bf16 v[58:61], v[134:137], v[184:187], v[58:61]
	v_mfma_f32_16x16x32_bf16 v[46:49], v[118:121], v[192:195], v[46:49]
	v_mfma_f32_16x16x32_bf16 v[42:45], v[134:137], v[192:195], v[42:45]
	v_mfma_f32_16x16x32_bf16 v[30:33], v[118:121], v[200:203], v[30:33]
	v_mfma_f32_16x16x32_bf16 v[26:29], v[134:137], v[200:203], v[26:29]
	v_mfma_f32_16x16x32_bf16 v[14:17], v[118:121], v[230:233], v[14:17]
	v_mfma_f32_16x16x32_bf16 v[10:13], v[134:137], v[230:233], v[10:13]
	s_barrier
; #define PG8_STAGE(bufoff, gbase, voff) do { _Pragma("unroll") for (int _i = 0; _i < 2; ++_i) \
;         __builtin_amdgcn_global_load_lds((const unsigned*)((const char*)(gbase) + (voff)[_i]), (PG8_LAS unsigned*)(lds + (bufoff) + ldsw + _i * 8192), 16, 0, 0); } while (0)
; #define PG8_LDA(dst, b, h) do { _Pragma("unroll") for (int m = 0; m < 4; ++m) _Pragma("unroll") for (int k = 0; k < 2; ++k) dst[m][k] = *(const PG8_LAS bf16x8*)(lds + PG8_SA(b, h) + aoff + m * 2048 + k * 1024); } while (0)
; #define PG8_LDB(dst, b, h) do { _Pragma("unroll") for (int n = 0; n < 2; ++n) _Pragma("unroll") for (int k = 0; k < 2; ++k) dst[n][k] = *(const PG8_LAS bf16x8*)(lds + PG8_SB(b, h) + boff + n * 2048 + k * 1024); } while (0)
; #define PG8_MMA(ai, bj, At, Bt) do { __builtin_amdgcn_s_setprio(1); _Pragma("unroll") for (int m = 0; m < 4; ++m) _Pragma("unroll") for (int n = 0; n < 2; ++n) _Pragma("unroll") for (int k = 0; k < 2; ++k) \
;         acc[ai][bj][m][n] = __builtin_amdgcn_mfma_f32_16x16x32_bf16(Bt[n][k], At[m][k], acc[ai][bj][m][n], 0, 0, 0); __builtin_amdgcn_s_setprio(0); } while (0)
; #define PG8_WAIT_V(n) asm volatile("s_waitcnt vmcnt(" #n ")" ::: "memory")
; #define PG8_WAIT_L(n) asm volatile("s_waitcnt lgkmcnt(" #n ")" ::: "memory")
; #define PG8_BAR __builtin_amdgcn_s_barrier()
; #define PG8_SCHED __builtin_amdgcn_sched_barrier(0)
; template <class Epi, class Sched, bool ALIGN_EPI = false, bool SP2 = false>
; __device__ __forceinline__ void gemm_phase(PG8_LAS unsigned char* lds, const Gemm g, const Sched& S, const Epi& E) {
;     ...
;             PG8_LDB(B0, 1, 0); PG8_LDB(B1, 1, 1); PG8_SCHED; PG8_LDA(At, 1, 0); PG8_STAGE(PG8_SA(0, 1), a2 + hstep, voffA);
;             PG8_WAIT_V(8); PG8_WAIT_L(0); PG8_BAR; PG8_MMA(0, 0, At, B0); PG8_MMA(0, 1, At, B1); PG8_BAR; PG8_SCHED;
;             PG8_LDA(At, 1, 1); PG8_STAGE(PG8_SB(1, 0), b3, voffB); PG8_STAGE(PG8_SB(1, 1), b3 + hstep, voffB); PG8_STAGE(PG8_SA(1, 0), a3, voffA);
;             PG8_WAIT_V(8); PG8_WAIT_L(0); PG8_BAR; PG8_MMA(1, 0, At, B0); PG8_MMA(1, 1, At, B1); PG8_BAR; PG8_SCHED;
	s_add_i32 s47, 0, 0x1c000
	ds_read_b128 v[114:117], v244
	ds_read_b128 v[118:121], v244 offset:1024
	ds_read_b128 v[130:133], v244 offset:2048
	ds_read_b128 v[134:137], v244 offset:3072
	s_add_u32 s42, s42, 0x80000
	s_addc_u32 s43, s43, 0
	s_mov_b32 m0, s10
	v_lshl_add_u64 v[238:239], s[42:43], 0, v[158:159]
	ds_read_b128 v[180:183], v178 offset:32768
	ds_read_b128 v[184:187], v178 offset:33792
	ds_read_b128 v[188:191], v178 offset:34816
	ds_read_b128 v[192:195], v178 offset:35840
	ds_read_b128 v[196:199], v178 offset:36864
	ds_read_b128 v[200:203], v178 offset:37888
	ds_read_b128 v[208:211], v178 offset:38912
	ds_read_b128 v[230:233], v178 offset:39936
	global_load_lds_dwordx4 v[238:239], off
	s_mov_b32 m0, s11
	v_lshl_add_u64 v[238:239], s[42:43], 0, v[156:157]
	global_load_lds_dwordx4 v[238:239], off
	s_waitcnt vmcnt(8)
	s_waitcnt lgkmcnt(0)
	s_barrier
	v_mfma_f32_16x16x32_bf16 v[142:145], v[114:117], v[180:183], v[142:145]
	v_mfma_f32_16x16x32_bf16 v[138:141], v[130:133], v[180:183], v[138:141]
	v_mfma_f32_16x16x32_bf16 v[110:113], v[114:117], v[188:191], v[110:113]
	v_mfma_f32_16x16x32_bf16 v[106:109], v[130:133], v[188:191], v[106:109]
	v_mfma_f32_16x16x32_bf16 v[94:97], v[114:117], v[196:199], v[94:97]
	v_mfma_f32_16x16x32_bf16 v[90:93], v[130:133], v[196:199], v[90:93]
	v_mfma_f32_16x16x32_bf16 v[78:81], v[114:117], v[208:211], v[78:81]
	v_mfma_f32_16x16x32_bf16 v[74:77], v[130:133], v[208:211], v[74:77]
	v_mfma_f32_16x16x32_bf16 v[142:145], v[118:121], v[184:187], v[142:145]
	v_mfma_f32_16x16x32_bf16 v[138:141], v[134:137], v[184:187], v[138:141]
	v_mfma_f32_16x16x32_bf16 v[110:113], v[118:121], v[192:195], v[110:113]
	v_mfma_f32_16x16x32_bf16 v[106:109], v[134:137], v[192:195], v[106:109]
	v_mfma_f32_16x16x32_bf16 v[94:97], v[118:121], v[200:203], v[94:97]
	v_mfma_f32_16x16x32_bf16 v[90:93], v[134:137], v[200:203], v[90:93]
	v_mfma_f32_16x16x32_bf16 v[78:81], v[118:121], v[230:233], v[78:81]
	v_mfma_f32_16x16x32_bf16 v[74:77], v[134:137], v[230:233], v[74:77]
	s_barrier
	s_add_i32 s42, s90, s6
	v_lshl_add_u64 v[204:205], v[204:205], 0, s[70:71]
	s_mov_b32 m0, s42
	ds_read_b128 v[180:183], v178 offset:49152
	ds_read_b128 v[184:187], v178 offset:50176
	ds_read_b128 v[188:191], v178 offset:51200
	ds_read_b128 v[192:195], v178 offset:52224
	ds_read_b128 v[196:199], v178 offset:53248
	ds_read_b128 v[200:203], v178 offset:54272
	ds_read_b128 v[208:211], v178 offset:55296
	ds_read_b128 v[230:233], v178 offset:56320
	global_load_lds_dwordx4 v[204:205], off
	s_add_i32 m0, s42, 0x2000
	s_add_u32 s40, s40, 0x80080
	v_lshl_add_u64 v[204:205], v[212:213], 0, s[70:71]
	s_addc_u32 s41, s41, 0
	s_add_i32 s42, s47, s6
	global_load_lds_dwordx4 v[204:205], off
	s_mov_b32 m0, s42
	v_lshl_add_u64 v[204:205], s[40:41], 0, v[0:1]
	global_load_lds_dwordx4 v[204:205], off
	s_add_i32 m0, s42, 0x2000
	v_lshl_add_u64 v[204:205], s[40:41], 0, v[154:155]
	global_load_lds_dwordx4 v[204:205], off
	s_mov_b32 m0, s13
	v_lshl_add_u64 v[204:205], v[234:235], 0, s[70:71]
	global_load_lds_dwordx4 v[204:205], off
	s_mov_b32 m0, s25
	v_lshl_add_u64 v[204:205], v[236:237], 0, s[70:71]
	global_load_lds_dwordx4 v[204:205], off
	s_waitcnt vmcnt(8)
	s_waitcnt lgkmcnt(0)
	s_barrier
	v_mfma_f32_16x16x32_bf16 v[62:65], v[114:117], v[180:183], v[62:65]
	v_mfma_f32_16x16x32_bf16 v[58:61], v[130:133], v[180:183], v[58:61]
	v_mfma_f32_16x16x32_bf16 v[46:49], v[114:117], v[188:191], v[46:49]
	v_mfma_f32_16x16x32_bf16 v[42:45], v[130:133], v[188:191], v[42:45]
	v_mfma_f32_16x16x32_bf16 v[30:33], v[114:117], v[196:199], v[30:33]
	v_mfma_f32_16x16x32_bf16 v[26:29], v[130:133], v[196:199], v[26:29]
	v_mfma_f32_16x16x32_bf16 v[14:17], v[114:117], v[208:211], v[14:17]
	v_mfma_f32_16x16x32_bf16 v[10:13], v[130:133], v[208:211], v[10:13]
	v_mfma_f32_16x16x32_bf16 v[62:65], v[118:121], v[184:187], v[62:65]
	v_mfma_f32_16x16x32_bf16 v[58:61], v[134:137], v[184:187], v[58:61]
	v_mfma_f32_16x16x32_bf16 v[46:49], v[118:121], v[192:195], v[46:49]
	v_mfma_f32_16x16x32_bf16 v[42:45], v[134:137], v[192:195], v[42:45]
	v_mfma_f32_16x16x32_bf16 v[30:33], v[118:121], v[200:203], v[30:33]
	v_mfma_f32_16x16x32_bf16 v[26:29], v[134:137], v[200:203], v[26:29]
	v_mfma_f32_16x16x32_bf16 v[14:17], v[118:121], v[230:233], v[14:17]
	v_mfma_f32_16x16x32_bf16 v[10:13], v[134:137], v[230:233], v[10:13]
	s_add_i32 s46, s46, 2
	s_add_u32 s34, s34, 0x100
	s_addc_u32 s35, s35, 0
	s_add_u32 s44, s44, 0x100
	s_addc_u32 s45, s45, 0
	s_cmp_gt_u32 s46, 29
	s_barrier
	s_cbranch_scc0 .Ltail_loop
	s_branch .Ltail_join
